# P1 unit order regrouped to 4 row tiles x 8 column tiles per XCD round; attention max tree shortened; skinny loads batched
# speedup vs baseline: 1.0084x; 1.0033x over previous
;     __host__ __device__ bool next(int i, Unit& u) const {
;     ...
;         int wgid = (int)L; { const int q = nwg / NXCD, r = nwg % NXCD, xcd = wgid % NXCD, off = wgid / NXCD; wgid = (xcd < r ? xcd * (q + 1) : r * (q + 1) + (xcd - r) * q) + off; }
;         const int nig = WGM * nN, gid = wgid / nig, fm = gid * WGM, gsz = (nM - fm) < WGM ? (nM - fm) : WGM;
;         u.pm = fm + ((wgid % nig) % gsz); u.pn = (wgid % nig) / gsz; return true;
.LBB0_183:
	s_ashr_i32 s10, s12, 3
	s_add_i32 s10, s29, s10
	s_ashr_i32 s11, s10, 31
	s_lshr_b32 s11, s11, 26
	s_add_i32 s11, s10, s11
	s_ashr_i32 s12, s11, 6
	s_andn2_b32 s11, s11, 63
	s_sub_i32 s10, s10, s11
	s_and_b32 s11, s10, 3
	s_lshl_b32 s12, s12, 2
	s_add_i32 s12, s12, s11
	s_lshr_b32 s10, s10, 2
	s_mov_b32 s13, 0

;     __host__ __device__ bool next(int i, Unit& u) const {
;     ...
;         int wgid = (int)L; { const int q = nwg / NXCD, r = nwg % NXCD, xcd = wgid % NXCD, off = wgid / NXCD; wgid = (xcd < r ? xcd * (q + 1) : r * (q + 1) + (xcd - r) * q) + off; }
;         const int nig = WGM * nN, gid = wgid / nig, fm = gid * WGM, gsz = (nM - fm) < WGM ? (nM - fm) : WGM;
;         u.pm = fm + ((wgid % nig) % gsz); u.pn = (wgid % nig) / gsz; return true;
.LBB0_195:
	s_ashr_i32 s6, s8, 3
	s_add_i32 s6, s11, s6
	s_ashr_i32 s7, s6, 31
	s_lshr_b32 s7, s7, 26
	s_add_i32 s7, s6, s7
	s_ashr_i32 s8, s7, 6
	s_lshl_b32 s8, s8, 2
	s_sub_i32 s9, 0x80, s8
	s_min_i32 s9, s9, 4
	s_abs_i32 s11, s9
	v_cvt_f32_u32_e32 v2, s11
	s_sub_i32 s33, 0, s11
	s_andn2_b32 s7, s7, 63
	s_sub_i32 s6, s6, s7
	v_rcp_iflag_f32_e32 v2, v2
	s_abs_i32 s7, s6
	s_xor_b32 s13, s6, s9
	s_ashr_i32 s13, s13, 31
	v_mul_f32_e32 v2, 0x4f7ffffe, v2
	v_cvt_u32_f32_e32 v2, v2
	s_nop 0
	v_readfirstlane_b32 s36, v2
	s_mul_i32 s33, s33, s36
	s_mul_hi_u32 s33, s36, s33
	s_add_i32 s36, s36, s33
	s_mul_hi_u32 s33, s7, s36
	s_mul_i32 s36, s33, s11
	s_sub_i32 s7, s7, s36
	s_add_i32 s37, s33, 1
	s_sub_i32 s36, s7, s11
	s_cmp_ge_u32 s7, s11
	s_cselect_b32 s33, s37, s33
	s_cselect_b32 s7, s36, s7
	s_add_i32 s36, s33, 1
	s_cmp_ge_u32 s7, s11
	s_cselect_b32 s7, s36, s33
	s_xor_b32 s7, s7, s13
	s_sub_i32 s36, s7, s13
	s_mul_i32 s7, s36, s9
	s_sub_i32 s6, s6, s7
	s_add_i32 s40, s8, s6
